# scan pass 1 S1c: waves 4-7 (longer cumulative-decay loops) run at raised priority until the stage barrier
# speedup vs baseline: 1.0121x; 1.0007x over previous
; #define LAS __attribute__((address_space(3)))
; __device__ __forceinline__ void scan_pass1(const ScanP& sp, int b, int h, int seg, LAS unsigned char* lds) {
;     ...
;         if (ci >= 0) {
;         __syncthreads();
;         {
;             const f32x4 r4 = *(const LAS f32x4*)(stash + tid * 12), v4 = *(const LAS f32x4*)(stash + tid * 12 + 4), kp = *(const LAS f32x4*)(stash + tid * 12 + 8);
;             f32x4 cl = {0.f, 0.f, 0.f, 0.f};
; #pragma unroll 2
;             for (int s4 = 0; s4 < w; ++s4) {
;                 const LAS float* lp_ = lwS + (4 * s4) * 64 + j4;
;                 const f32x4 x0 = *(const LAS f32x4*)lp_, x1 = *(const LAS f32x4*)(lp_ + 64), x2 = *(const LAS f32x4*)(lp_ + 128), x3 = *(const LAS f32x4*)(lp_ + 192);
;                 cl += (x0 + x1) + (x2 + x3);
;             }
; #pragma unroll
;             for (int q = 0; q < 4; ++q) { const int s = 4 * w + q; const f32x4 x = *(const LAS f32x4*)(lwS + s * 64 + j4); if (s <= tt) cl += x; }
.Ls1c_nobar:
	s_and_b64 vcc, exec, s[56:57]
	s_cbranch_vccz .Ls1c_noprio
	s_setprio 2

; __device__ __forceinline__ void scan_pass1(const ScanP& sp, int b, int h, int seg, LAS unsigned char* lds) {
;     ...
;             f32x4 ein, eex, einv;
; #pragma unroll
;             for (int e = 0; e < 4; ++e) { ein[e] = ex2(cl[e]); eex[e] = ex2(cl[e] - lw[e]); einv[e] = __builtin_amdgcn_rcpf(ein[e]); }
;             const f32x4 kkt = kkn * eex, rt = r4 * ein, kh = kp * einv, bh = bb * einv;
;             u32x2 o;
;             o.x = pk2(kkt[0], kkt[1]); o.y = pk2(kkt[2], kkt[3]); *(LAS u32x2*)(lds + O_KK + (tt * 72 + j4) * 2) = o;
;             o.x = pk2(rt[0], rt[1]); o.y = pk2(rt[2], rt[3]); *(LAS u32x2*)(lds + O_R + (tt * 72 + j4) * 2) = o;
;             o.x = pk2(kh[0], kh[1]); o.y = pk2(kh[2], kh[3]); *(LAS u32x2*)(lds + O_K + (tt * 72 + j4) * 2) = o;
;             const unsigned k01 = o.x, k23 = o.y;
;             o.x = pk2(bh[0], bh[1]); o.y = pk2(bh[2], bh[3]); *(LAS u32x2*)(lds + O_B + (tt * 72 + j4) * 2) = o;
;             const unsigned nb01 = pk2(-bh[0], -bh[1]), nb23 = pk2(-bh[2], -bh[3]);
;             const unsigned v01 = pk2(v4[0], v4[1]), v23 = pk2(v4[2], v4[3]);
;             LAS unsigned short* kt = (LAS unsigned short*)(lds + O_KT) + j4 * 40 + tt;
;             kt[0] = (unsigned short)(k01 & 0xffffu); kt[40] = (unsigned short)(k01 >> 16); kt[80] = (unsigned short)(k23 & 0xffffu); kt[120] = (unsigned short)(k23 >> 16);
;             LAS unsigned short* bt = (LAS unsigned short*)(lds + O_BT) + j4 * 40 + tt;
;             bt[0] = (unsigned short)(nb01 & 0xffffu); bt[40] = (unsigned short)(nb01 >> 16); bt[80] = (unsigned short)(nb23 & 0xffffu); bt[120] = (unsigned short)(nb23 >> 16);
;             LAS unsigned short* vt = (LAS unsigned short*)(lds + O_VT) + j4 * 40 + tt;
;             vt[0] = (unsigned short)(v01 & 0xffffu); vt[40] = (unsigned short)(v01 >> 16); vt[80] = (unsigned short)(v23 & 0xffffu); vt[120] = (unsigned short)(v23 >> 16);
;             if (tt == 31) *(LAS f32x4*)(gam + j4) = ein;
;         }
;         __syncthreads();
;         if (w < 4) {
; #pragma unroll
;             for (int i = 0; i < 16; ++i) { P1[i] = 0.f; P2[i] = 0.f; }
; #pragma unroll
;             for (int jb = 0; jb < 2; ++jb)
; #pragma unroll
;                 for (int s = 0; s < 2; ++s) {
;                     const bf16x8 hb = pack8(Hacc[jb], s);
;                     const int off = (ln * 72 + 32 * jb + 16 * s + 4 * hh) * 2;
.LBB0_266:
	s_or_b64 exec, exec, s[0:1]
	v_sub_f32_e32 v0, v80, v100
	v_exp_f32_e32 v104, v80
	v_exp_f32_e32 v105, v81
	v_exp_f32_e32 v2, v0
	v_sub_f32_e32 v0, v81, v101
	v_exp_f32_e32 v106, v82
	v_exp_f32_e32 v107, v83
	v_exp_f32_e32 v3, v0
	v_sub_f32_e32 v0, v82, v102
	v_exp_f32_e32 v82, v0
	v_sub_f32_e32 v0, v83, v103
	v_exp_f32_e32 v83, v0
	v_rcp_f32_e32 v80, v104
	v_rcp_f32_e32 v81, v105
	v_rcp_f32_e32 v110, v106
	v_rcp_f32_e32 v111, v107
	v_pk_mul_f32 v[82:83], v[132:133], v[82:83]
	v_pk_mul_f32 v[2:3], v[130:131], v[2:3]
	s_waitcnt lgkmcnt(0)
	v_pk_mul_f32 v[78:79], v[78:79], v[106:107]
	v_pk_mul_f32 v[76:77], v[76:77], v[104:105]
	v_pk_mul_f32 v[74:75], v[74:75], v[110:111]
	v_pk_mul_f32 v[72:73], v[72:73], v[80:81]
	v_pk_mul_f32 v[110:111], v[136:137], v[110:111]
	v_pk_mul_f32 v[80:81], v[134:135], v[80:81]
	v_cvt_pk_bf16_f32 v2, v2, v3
	v_cvt_pk_bf16_f32 v3, v82, v83
	v_add_u32_e32 v0, 0, v163
	v_cvt_pk_bf16_f32 v76, v76, v77
	v_cvt_pk_bf16_f32 v77, v78, v79
	ds_write2st64_b64 v0, v[2:3], v[76:77] offset0:64 offset1:73
	v_cvt_pk_bf16_f32 v2, v72, v73
	v_cvt_pk_bf16_f32 v3, v74, v75
	v_cvt_pk_bf16_f32 v72, v80, v81
	v_cvt_pk_bf16_f32 v73, v110, v111
	ds_write2st64_b64 v0, v[2:3], v[72:73] offset0:82 offset1:91
	v_xor_b32_e32 v0, 0x80000000, v81
	v_xor_b32_e32 v72, 0x80000000, v80
	v_cvt_pk_bf16_f32 v0, v72, v0
	v_xor_b32_e32 v72, 0x80000000, v110
	v_xor_b32_e32 v73, 0x80000000, v111
	v_cvt_pk_bf16_f32 v72, v72, v73
	v_cvt_pk_bf16_f32 v68, v68, v69
	v_cvt_pk_bf16_f32 v69, v70, v71
	v_mov_b32_e32 v250, v0
	v_mov_b32_e32 v251, v72
	v_lshlrev_b32_e32 v245, 3, v210
	v_and_b32_e32 v245, 48, v245
	v_mov_b32_e32 v246, v245
	v_mad_u32_u24 v247, v246, 5, v164
	v_lshrrev_b64 v[230:231], v246, v[2:3]
	v_lshrrev_b64 v[232:233], v246, v[250:251]
	v_lshrrev_b64 v[234:235], v246, v[68:69]
	ds_write_b16 v247, v230 offset:51200
	ds_write_b16 v247, v232 offset:56320
	ds_write_b16 v247, v234 offset:61440
	v_add_u32_e32 v246, 16, v245
	v_and_b32_e32 v246, 48, v246
	v_mad_u32_u24 v247, v246, 5, v164
	v_lshrrev_b64 v[230:231], v246, v[2:3]
	v_lshrrev_b64 v[232:233], v246, v[250:251]
	v_lshrrev_b64 v[234:235], v246, v[68:69]
	ds_write_b16 v247, v230 offset:51200
	ds_write_b16 v247, v232 offset:56320
	ds_write_b16 v247, v234 offset:61440
	v_add_u32_e32 v246, 32, v245
	v_and_b32_e32 v246, 48, v246
	v_mad_u32_u24 v247, v246, 5, v164
	v_lshrrev_b64 v[230:231], v246, v[2:3]
	v_lshrrev_b64 v[232:233], v246, v[250:251]
	v_lshrrev_b64 v[234:235], v246, v[68:69]
	ds_write_b16 v247, v230 offset:51200
	ds_write_b16 v247, v232 offset:56320
	ds_write_b16 v247, v234 offset:61440
	v_add_u32_e32 v246, 48, v245
	v_and_b32_e32 v246, 48, v246
	v_mad_u32_u24 v247, v246, 5, v164
	v_lshrrev_b64 v[230:231], v246, v[2:3]
	v_lshrrev_b64 v[232:233], v246, v[250:251]
	v_lshrrev_b64 v[234:235], v246, v[68:69]
	ds_write_b16 v247, v230 offset:51200
	ds_write_b16 v247, v232 offset:56320
	ds_write_b16 v247, v234 offset:61440
	s_and_saveexec_b64 s[0:1], s[52:53]
	ds_write_b128 v165, v[104:107]
	s_or_b64 exec, exec, s[0:1]
	v_mul_u32_u24_e32 v0, 0x90, v189
	s_andn2_b64 vcc, exec, s[56:57]
	s_mov_b64 s[0:1], -1
	s_waitcnt lgkmcnt(0)
	s_setprio 0
	s_barrier
	s_cbranch_vccnz .LBB0_284
	v_lshl_add_u32 v2, v188, 4, v0
	v_add_u32_e32 v3, s65, v2
	v_add_u32_e32 v2, s77, v2
	ds_read_b128 v[68:71], v3
	ds_read_b128 v[72:75], v2
	ds_read_b128 v[104:107], v3 offset:32
	ds_read_b128 v[110:113], v2 offset:32
	ds_read_b128 v[230:233], v3 offset:64
	ds_read_b128 v[234:237], v2 offset:64
	ds_read_b128 v[238:241], v3 offset:96
	ds_read_b128 v[242:245], v2 offset:96
	s_mov_b64 s[78:79], -1
	s_and_b64 vcc, exec, s[72:73]
	s_waitcnt lgkmcnt(6)
	v_mfma_f32_32x32x16_bf16 v[68:83], v[68:71], v[72:75], 0
	s_waitcnt lgkmcnt(4)
	v_mfma_f32_32x32x16_bf16 v[68:83], v[104:107], v[110:113], v[68:83]
	s_waitcnt lgkmcnt(2)
	v_mfma_f32_32x32x16_bf16 v[68:83], v[230:233], v[234:237], v[68:83]
	v_lshlrev_b32_e32 v2, 2, v188
	v_or_b32_e32 v117, 2, v2
	v_or_b32_e32 v116, 3, v2
	v_add_u32_e32 v115, 8, v2
	v_add_u32_e32 v109, 10, v2
	v_add_u32_e32 v3, 11, v2
	s_waitcnt lgkmcnt(0)
	v_mfma_f32_32x32x16_bf16 v[68:83], v[238:241], v[242:245], v[68:83]
	v_add_u32_e32 v113, 9, v2
	v_add_u32_e32 v111, 16, v2
	v_add_u32_e32 v106, 17, v2
	v_add_u32_e32 v110, 18, v2
	v_add_u32_e32 v104, 19, v2
	v_add_u32_e32 v114, 24, v2
	v_add_u32_e32 v112, 25, v2
	v_add_u32_e32 v107, 26, v2
	v_add_u32_e32 v105, 27, v2
	v_cmp_lt_i32_e64 s[40:41], v2, v189
	v_cmp_lt_i32_e64 s[50:51], v117, v189
	v_cmp_lt_i32_e64 s[48:49], v116, v189
	v_cmp_lt_i32_e64 s[46:47], v115, v189
	v_cmp_lt_i32_e64 s[44:45], v113, v189
	v_cmp_lt_i32_e64 s[42:43], v109, v189
	v_cmp_lt_i32_e64 s[38:39], v3, v189
	v_cmp_lt_i32_e64 s[36:37], v111, v189
	v_cmp_lt_i32_e64 s[34:35], v106, v189
	v_cmp_lt_i32_e64 s[30:31], v110, v189
	v_cmp_lt_i32_e64 s[28:29], v104, v189
	v_cmp_lt_i32_e64 s[26:27], v114, v189
	v_cmp_lt_i32_e64 s[24:25], v112, v189
	v_cmp_lt_i32_e64 s[22:23], v107, v189
	v_cmp_lt_i32_e64 s[0:1], v105, v189
	s_cbranch_vccz .LBB0_271
; #define LAS __attribute__((address_space(3)))
; __device__ __forceinline__ unsigned pk2(float lo, float hi) { f32x2 v = {lo, hi}; bf16x2_t b = __builtin_convertvector(v, bf16x2_t); return __builtin_bit_cast(unsigned, b); }
; __device__ __forceinline__ void scan_pass1(const ScanP& sp, int b, int h, int seg, LAS unsigned char* lds) {
;     ...
;                 const int oo = (job == 0) ? O_MK : (job == 2) ? O_NK : O_NB;
; #pragma unroll
;                 for (int g = 0; g < 4; ++g) {
;                     float z[4];
; #pragma unroll
;                     for (int e = 0; e < 4; ++e) {
;                         const int s = 8 * g + 4 * hh + e;
;                         const bool keep = (job == 0) ? (s < ln) : (s <= ln);
;                         float v = keep ? Z[4 * g + e] : 0.f; if (job == 3) v = -v; z[e] = v;
;                     }
;                     u32x2 o; o.x = pk2(z[0], z[1]); o.y = pk2(z[2], z[3]);
;                     *(LAS u32x2*)(lds + oo + (ln * 40 + 8 * g + 4 * hh) * 2) = o;
;                 }
	v_lshlrev_b32_e32 v118, 3, v188
	v_mul_u32_u24_e32 v119, 0x50, v189
	v_cmp_le_i32_e32 vcc, v2, v189
	v_add3_u32 v121, s33, v118, v119
	v_cndmask_b32_e64 v118, 0, 1, s[40:41]
	v_cndmask_b32_e64 v119, 0, 1, vcc
	v_cndmask_b32_e64 v118, v119, v118, s[4:5]
	v_and_b32_e32 v118, 1, v118
	v_cmp_eq_u32_e32 vcc, 1, v118
	v_or_b32_e32 v119, v2, v166
	v_cndmask_b32_e64 v123, 0, 1, s[50:51]
	v_cndmask_b32_e32 v118, 0, v68, vcc
	v_cmp_gt_i32_e32 vcc, v189, v119
	v_cndmask_b32_e64 v118, v118, -v118, s[74:75]
	s_mov_b64 s[78:79], 0
	v_cndmask_b32_e32 v119, 0, v69, vcc
	v_cmp_le_i32_e32 vcc, v117, v189
	v_cndmask_b32_e64 v119, v119, -v119, s[74:75]
	v_cvt_pk_bf16_f32 v118, v118, v119
	v_cndmask_b32_e64 v150, 0, 1, vcc
	v_cndmask_b32_e64 v123, v150, v123, s[4:5]
	v_and_b32_e32 v123, 1, v123
	v_cmp_eq_u32_e32 vcc, 1, v123
	v_cndmask_b32_e64 v150, 0, 1, s[48:49]
	s_nop 0
	v_cndmask_b32_e32 v123, 0, v70, vcc
	v_cmp_le_i32_e32 vcc, v116, v189
	v_cndmask_b32_e64 v123, v123, -v123, s[74:75]
	s_nop 0
	v_cndmask_b32_e64 v151, 0, 1, vcc
	v_cndmask_b32_e64 v150, v151, v150, s[4:5]
	v_and_b32_e32 v150, 1, v150
	v_cmp_eq_u32_e32 vcc, 1, v150
	s_nop 1
	v_cndmask_b32_e32 v150, 0, v71, vcc
	v_cndmask_b32_e64 v150, v150, -v150, s[74:75]
	v_cmp_le_i32_e32 vcc, v115, v189
	v_cvt_pk_bf16_f32 v119, v123, v150
	v_cndmask_b32_e64 v123, 0, 1, s[46:47]
	v_cndmask_b32_e64 v150, 0, 1, vcc
	v_cndmask_b32_e64 v123, v150, v123, s[4:5]
	v_and_b32_e32 v123, 1, v123
	v_cmp_eq_u32_e32 vcc, 1, v123
	v_cndmask_b32_e64 v150, 0, 1, s[44:45]
	s_nop 0
	v_cndmask_b32_e32 v123, 0, v72, vcc
	v_cmp_le_i32_e32 vcc, v113, v189
	v_cndmask_b32_e64 v123, v123, -v123, s[74:75]
	s_nop 0
	v_cndmask_b32_e64 v151, 0, 1, vcc
	v_cndmask_b32_e64 v150, v151, v150, s[4:5]
	v_and_b32_e32 v150, 1, v150
	v_cmp_eq_u32_e32 vcc, 1, v150
	v_cndmask_b32_e64 v151, 0, 1, s[42:43]
	s_nop 0
	v_cndmask_b32_e32 v150, 0, v73, vcc
	v_cmp_le_i32_e32 vcc, v109, v189
	v_cndmask_b32_e64 v150, v150, -v150, s[74:75]
	v_cvt_pk_bf16_f32 v150, v123, v150
	v_cndmask_b32_e64 v152, 0, 1, vcc
	v_cndmask_b32_e64 v151, v152, v151, s[4:5]
	v_and_b32_e32 v151, 1, v151
	v_cmp_eq_u32_e32 vcc, 1, v151
	v_cndmask_b32_e64 v152, 0, 1, s[38:39]
	s_nop 0
	v_cndmask_b32_e32 v151, 0, v74, vcc
	v_cmp_le_i32_e32 vcc, v3, v189
	v_cndmask_b32_e64 v151, v151, -v151, s[74:75]
	s_nop 0
	v_cndmask_b32_e64 v153, 0, 1, vcc
	v_cndmask_b32_e64 v152, v153, v152, s[4:5]
	v_and_b32_e32 v152, 1, v152
	v_cmp_eq_u32_e32 vcc, 1, v152
	s_nop 1
	v_cndmask_b32_e32 v152, 0, v75, vcc
	v_cndmask_b32_e64 v152, v152, -v152, s[74:75]
	v_cvt_pk_bf16_f32 v151, v151, v152
	v_cmp_le_i32_e32 vcc, v111, v189
	ds_write2_b64 v121, v[118:119], v[150:151] offset1:2
	v_cndmask_b32_e64 v118, 0, 1, s[36:37]
	v_cndmask_b32_e64 v119, 0, 1, vcc
	v_cndmask_b32_e64 v118, v119, v118, s[4:5]
	v_and_b32_e32 v118, 1, v118
	v_cmp_eq_u32_e32 vcc, 1, v118
	v_cndmask_b32_e64 v119, 0, 1, s[34:35]
	s_nop 0
	v_cndmask_b32_e32 v118, 0, v76, vcc
	v_cmp_le_i32_e32 vcc, v106, v189
	v_cndmask_b32_e64 v118, v118, -v118, s[74:75]
	s_nop 0
	v_cndmask_b32_e64 v123, 0, 1, vcc
	v_cndmask_b32_e64 v119, v123, v119, s[4:5]
	v_and_b32_e32 v119, 1, v119
	v_cmp_eq_u32_e32 vcc, 1, v119
	v_cndmask_b32_e64 v123, 0, 1, s[30:31]
	s_nop 0
	v_cndmask_b32_e32 v119, 0, v77, vcc
	v_cmp_le_i32_e32 vcc, v110, v189
	v_cndmask_b32_e64 v119, v119, -v119, s[74:75]
	v_cvt_pk_bf16_f32 v118, v118, v119
	v_cndmask_b32_e64 v150, 0, 1, vcc
	v_cndmask_b32_e64 v123, v150, v123, s[4:5]
	v_and_b32_e32 v123, 1, v123
	v_cmp_eq_u32_e32 vcc, 1, v123
	v_cndmask_b32_e64 v150, 0, 1, s[28:29]
	s_nop 0
	v_cndmask_b32_e32 v123, 0, v78, vcc
	v_cmp_le_i32_e32 vcc, v104, v189
	v_cndmask_b32_e64 v123, v123, -v123, s[74:75]
	s_nop 0
	v_cndmask_b32_e64 v151, 0, 1, vcc
	v_cndmask_b32_e64 v150, v151, v150, s[4:5]
	v_and_b32_e32 v150, 1, v150
	v_cmp_eq_u32_e32 vcc, 1, v150
	s_nop 1
	v_cndmask_b32_e32 v150, 0, v79, vcc
	v_cndmask_b32_e64 v150, v150, -v150, s[74:75]
	v_cmp_le_i32_e32 vcc, v114, v189
	v_cvt_pk_bf16_f32 v119, v123, v150
	v_cndmask_b32_e64 v123, 0, 1, s[26:27]
	v_cndmask_b32_e64 v150, 0, 1, vcc
	v_cndmask_b32_e64 v123, v150, v123, s[4:5]
	v_and_b32_e32 v123, 1, v123
	v_cmp_eq_u32_e32 vcc, 1, v123
	v_cndmask_b32_e64 v150, 0, 1, s[24:25]
	s_nop 0
	v_cndmask_b32_e32 v123, 0, v80, vcc
	v_cmp_le_i32_e32 vcc, v112, v189
	v_cndmask_b32_e64 v123, v123, -v123, s[74:75]
	s_nop 0
	v_cndmask_b32_e64 v151, 0, 1, vcc
	v_cndmask_b32_e64 v150, v151, v150, s[4:5]
	v_and_b32_e32 v150, 1, v150
	v_cmp_eq_u32_e32 vcc, 1, v150
	v_cndmask_b32_e64 v151, 0, 1, s[22:23]
	s_nop 0
	v_cndmask_b32_e32 v150, 0, v81, vcc
	v_cmp_le_i32_e32 vcc, v107, v189
	v_cndmask_b32_e64 v150, v150, -v150, s[74:75]
	v_cvt_pk_bf16_f32 v150, v123, v150
	v_cndmask_b32_e64 v152, 0, 1, vcc
	v_cndmask_b32_e64 v151, v152, v151, s[4:5]
	v_and_b32_e32 v151, 1, v151
	v_cmp_eq_u32_e32 vcc, 1, v151
	v_cndmask_b32_e64 v152, 0, 1, s[0:1]
	s_nop 0
	v_cndmask_b32_e32 v151, 0, v82, vcc
	v_cmp_le_i32_e32 vcc, v105, v189
	v_cndmask_b32_e64 v151, v151, -v151, s[74:75]
	s_nop 0
	v_cndmask_b32_e64 v153, 0, 1, vcc
	v_cndmask_b32_e64 v152, v153, v152, s[4:5]
	v_and_b32_e32 v152, 1, v152
	v_cmp_eq_u32_e32 vcc, 1, v152
	s_nop 1
	v_cndmask_b32_e32 v152, 0, v83, vcc
	v_cndmask_b32_e64 v152, v152, -v152, s[74:75]
	v_cvt_pk_bf16_f32 v151, v151, v152
	ds_write2_b64 v121, v[118:119], v[150:151] offset0:4 offset1:6
